# EpiResid epilogue (FFN-down / out-proj residual update): v_permlane16_swap puts 8 consecutive columns per lane, dwordx4 residual loads and stores, loads of the second half issued as registers free up
# speedup vs baseline: 1.0874x; 1.0161x over previous
.LBB0_947:
	s_lshl_b32 s2, s19, 8
	s_mov_b64 s[12:13], s[26:27]
	v_readlane_b32 s0, v251, 20
	v_readlane_b32 s1, v251, 21
	v_and_b32_e32 v140, 0x60, v191
	v_and_b32_e32 v141, 16, v209
	v_and_b32_e32 v142, 32, v209
	v_lshrrev_b32_e32 v142, 2, v142
	v_or3_b32 v140, v140, v141, v142
	v_lshl_or_b32 v140, s18, 8, v140
	v_add_u32_e32 v141, s2, v173
	v_lshlrev_b32_e32 v142, 11, v141
	v_lshl_add_u32 v136, v140, 1, v142
	v_lshlrev_b32_e32 v142, 12, v141
	v_lshl_add_u32 v137, v140, 2, v142
	v_xor_b32_e32 v138, 16, v209
	v_xor_b32_e32 v139, 32, v209
	v_lshlrev_b32_e32 v138, 2, v138
	v_lshlrev_b32_e32 v139, 2, v139
	s_and_b64 vcc, exec, s[26:27]
	s_cbranch_vccnz .Lresid_fin
	s_add_u32 s10, s0, 0x0
	s_addc_u32 s11, s1, 0
	global_load_dwordx4 v[140:143], v136, s[10:11]
	global_load_dwordx4 v[144:147], v136, s[10:11] offset:256
	s_add_u32 s10, s0, 0x8000
	s_addc_u32 s11, s1, 0
	global_load_dwordx4 v[148:151], v136, s[10:11]
	global_load_dwordx4 v[152:155], v136, s[10:11] offset:256
	s_add_u32 s10, s0, 0x10000
	s_addc_u32 s11, s1, 0
	global_load_dwordx4 v[156:159], v136, s[10:11]
	global_load_dwordx4 v[160:163], v136, s[10:11] offset:256
	s_add_u32 s10, s0, 0x18000
	s_addc_u32 s11, s1, 0
	global_load_dwordx4 v[164:167], v136, s[10:11]
	global_load_dwordx4 v[174:177], v136, s[10:11] offset:256
	s_waitcnt vmcnt(7)
	v_permlane16_swap_b32_e32 v126, v122
	v_permlane16_swap_b32_e32 v127, v123
	v_permlane16_swap_b32_e32 v128, v124
	v_permlane16_swap_b32_e32 v129, v125
	v_lshlrev_b32_e32 v178, 16, v140
	v_and_b32_e32 v179, 0xffff0000, v140
	v_lshlrev_b32_e32 v180, 16, v141
	v_and_b32_e32 v181, 0xffff0000, v141
	v_lshlrev_b32_e32 v182, 16, v142
	v_and_b32_e32 v183, 0xffff0000, v142
	v_lshlrev_b32_e32 v184, 16, v143
	v_and_b32_e32 v185, 0xffff0000, v143
	v_pk_fma_f32 v[126:127], s[14:15], v[126:127], v[178:179]
	v_pk_fma_f32 v[128:129], s[14:15], v[128:129], v[180:181]
	v_pk_fma_f32 v[122:123], s[14:15], v[122:123], v[182:183]
	v_pk_fma_f32 v[124:125], s[14:15], v[124:125], v[184:185]
	s_add_u32 s10, s0, 0x0
	s_addc_u32 s11, s1, 0
	v_cvt_pk_bf16_f32 v140, v126, v127
	v_cvt_pk_bf16_f32 v141, v128, v129
	v_cvt_pk_bf16_f32 v142, v122, v123
	v_cvt_pk_bf16_f32 v143, v124, v125
	global_store_dwordx4 v136, v[140:143], s[10:11]
	s_add_u32 s10, s0, 0x40000
	s_addc_u32 s11, s1, 0
	global_load_dwordx4 v[126:129], v136, s[10:11]
	v_lshlrev_b32_e32 v178, 16, v140
	v_lshlrev_b32_e32 v179, 16, v141
	v_and_b32_e32 v180, 0xffff0000, v140
	v_and_b32_e32 v181, 0xffff0000, v141
	v_lshlrev_b32_e32 v182, 16, v142
	v_lshlrev_b32_e32 v183, 16, v143
	v_and_b32_e32 v184, 0xffff0000, v142
	v_and_b32_e32 v185, 0xffff0000, v143
	v_pk_mul_f32 v[180:181], v[180:181], v[180:181]
	v_pk_mul_f32 v[184:185], v[184:185], v[184:185]
	v_pk_fma_f32 v[178:179], v[178:179], v[178:179], v[180:181]
	v_pk_fma_f32 v[182:183], v[182:183], v[182:183], v[184:185]
	s_nop 0
	v_add_f32_e32 v178, v178, v179
	v_add_f32_e32 v182, v182, v183
	v_add_f32_e32 v186, v178, v182
	s_waitcnt vmcnt(8)
	v_permlane16_swap_b32_e32 v118, v114
	v_permlane16_swap_b32_e32 v119, v115
	v_permlane16_swap_b32_e32 v120, v116
	v_permlane16_swap_b32_e32 v121, v117
	v_lshlrev_b32_e32 v178, 16, v144
	v_and_b32_e32 v179, 0xffff0000, v144
	v_lshlrev_b32_e32 v180, 16, v145
	v_and_b32_e32 v181, 0xffff0000, v145
	v_lshlrev_b32_e32 v182, 16, v146
	v_and_b32_e32 v183, 0xffff0000, v146
	v_lshlrev_b32_e32 v184, 16, v147
	v_and_b32_e32 v185, 0xffff0000, v147
	v_pk_fma_f32 v[118:119], s[14:15], v[118:119], v[178:179]
	v_pk_fma_f32 v[120:121], s[14:15], v[120:121], v[180:181]
	v_pk_fma_f32 v[114:115], s[14:15], v[114:115], v[182:183]
	v_pk_fma_f32 v[116:117], s[14:15], v[116:117], v[184:185]
	s_add_u32 s10, s0, 0x0
	s_addc_u32 s11, s1, 0
	v_cvt_pk_bf16_f32 v144, v118, v119
	v_cvt_pk_bf16_f32 v145, v120, v121
	v_cvt_pk_bf16_f32 v146, v114, v115
	v_cvt_pk_bf16_f32 v147, v116, v117
	global_store_dwordx4 v136, v[144:147], s[10:11] offset:256
	s_add_u32 s10, s0, 0x40000
	s_addc_u32 s11, s1, 0
	global_load_dwordx4 v[118:121], v136, s[10:11] offset:256
	v_lshlrev_b32_e32 v178, 16, v144
	v_lshlrev_b32_e32 v179, 16, v145
	v_and_b32_e32 v180, 0xffff0000, v144
	v_and_b32_e32 v181, 0xffff0000, v145
	v_lshlrev_b32_e32 v182, 16, v146
	v_lshlrev_b32_e32 v183, 16, v147
	v_and_b32_e32 v184, 0xffff0000, v146
	v_and_b32_e32 v185, 0xffff0000, v147
	v_pk_mul_f32 v[180:181], v[180:181], v[180:181]
	v_pk_mul_f32 v[184:185], v[184:185], v[184:185]
	v_pk_fma_f32 v[178:179], v[178:179], v[178:179], v[180:181]
	v_pk_fma_f32 v[182:183], v[182:183], v[182:183], v[184:185]
	s_nop 0
	v_add_f32_e32 v178, v178, v179
	v_add_f32_e32 v182, v182, v183
	v_add_f32_e32 v186, v186, v178
	v_add_f32_e32 v186, v186, v182
	s_waitcnt vmcnt(9)
	v_permlane16_swap_b32_e32 v110, v106
	v_permlane16_swap_b32_e32 v111, v107
	v_permlane16_swap_b32_e32 v112, v108
	v_permlane16_swap_b32_e32 v113, v109
	v_lshlrev_b32_e32 v178, 16, v148
	v_and_b32_e32 v179, 0xffff0000, v148
	v_lshlrev_b32_e32 v180, 16, v149
	v_and_b32_e32 v181, 0xffff0000, v149
	v_lshlrev_b32_e32 v182, 16, v150
	v_and_b32_e32 v183, 0xffff0000, v150
	v_lshlrev_b32_e32 v184, 16, v151
	v_and_b32_e32 v185, 0xffff0000, v151
	v_pk_fma_f32 v[110:111], s[14:15], v[110:111], v[178:179]
	v_pk_fma_f32 v[112:113], s[14:15], v[112:113], v[180:181]
	v_pk_fma_f32 v[106:107], s[14:15], v[106:107], v[182:183]
	v_pk_fma_f32 v[108:109], s[14:15], v[108:109], v[184:185]
	s_add_u32 s10, s0, 0x8000
	s_addc_u32 s11, s1, 0
	v_cvt_pk_bf16_f32 v148, v110, v111
	v_cvt_pk_bf16_f32 v149, v112, v113
	v_cvt_pk_bf16_f32 v150, v106, v107
	v_cvt_pk_bf16_f32 v151, v108, v109
	global_store_dwordx4 v136, v[148:151], s[10:11]
	s_add_u32 s10, s0, 0x48000
	s_addc_u32 s11, s1, 0
	global_load_dwordx4 v[110:113], v136, s[10:11]
	v_lshlrev_b32_e32 v178, 16, v148
	v_lshlrev_b32_e32 v179, 16, v149
	v_and_b32_e32 v180, 0xffff0000, v148
	v_and_b32_e32 v181, 0xffff0000, v149
	v_lshlrev_b32_e32 v182, 16, v150
	v_lshlrev_b32_e32 v183, 16, v151
	v_and_b32_e32 v184, 0xffff0000, v150
	v_and_b32_e32 v185, 0xffff0000, v151
	v_pk_mul_f32 v[180:181], v[180:181], v[180:181]
	v_pk_mul_f32 v[184:185], v[184:185], v[184:185]
	v_pk_fma_f32 v[178:179], v[178:179], v[178:179], v[180:181]
	v_pk_fma_f32 v[182:183], v[182:183], v[182:183], v[184:185]
	s_nop 0
	v_add_f32_e32 v178, v178, v179
	v_add_f32_e32 v182, v182, v183
	v_add_f32_e32 v187, v178, v182
	s_waitcnt vmcnt(10)
	v_permlane16_swap_b32_e32 v102, v98
	v_permlane16_swap_b32_e32 v103, v99
	v_permlane16_swap_b32_e32 v104, v100
	v_permlane16_swap_b32_e32 v105, v101
	v_lshlrev_b32_e32 v178, 16, v152
	v_and_b32_e32 v179, 0xffff0000, v152
	v_lshlrev_b32_e32 v180, 16, v153
	v_and_b32_e32 v181, 0xffff0000, v153
	v_lshlrev_b32_e32 v182, 16, v154
	v_and_b32_e32 v183, 0xffff0000, v154
	v_lshlrev_b32_e32 v184, 16, v155
	v_and_b32_e32 v185, 0xffff0000, v155
	v_pk_fma_f32 v[102:103], s[14:15], v[102:103], v[178:179]
	v_pk_fma_f32 v[104:105], s[14:15], v[104:105], v[180:181]
	v_pk_fma_f32 v[98:99], s[14:15], v[98:99], v[182:183]
	v_pk_fma_f32 v[100:101], s[14:15], v[100:101], v[184:185]
	s_add_u32 s10, s0, 0x8000
	s_addc_u32 s11, s1, 0
	v_cvt_pk_bf16_f32 v152, v102, v103
	v_cvt_pk_bf16_f32 v153, v104, v105
	v_cvt_pk_bf16_f32 v154, v98, v99
	v_cvt_pk_bf16_f32 v155, v100, v101
	global_store_dwordx4 v136, v[152:155], s[10:11] offset:256
	s_add_u32 s10, s0, 0x48000
	s_addc_u32 s11, s1, 0
	global_load_dwordx4 v[102:105], v136, s[10:11] offset:256
	v_lshlrev_b32_e32 v178, 16, v152
	v_lshlrev_b32_e32 v179, 16, v153
	v_and_b32_e32 v180, 0xffff0000, v152
	v_and_b32_e32 v181, 0xffff0000, v153
	v_lshlrev_b32_e32 v182, 16, v154
	v_lshlrev_b32_e32 v183, 16, v155
	v_and_b32_e32 v184, 0xffff0000, v154
	v_and_b32_e32 v185, 0xffff0000, v155
	v_pk_mul_f32 v[180:181], v[180:181], v[180:181]
	v_pk_mul_f32 v[184:185], v[184:185], v[184:185]
	v_pk_fma_f32 v[178:179], v[178:179], v[178:179], v[180:181]
	v_pk_fma_f32 v[182:183], v[182:183], v[182:183], v[184:185]
	s_nop 0
	v_add_f32_e32 v178, v178, v179
	v_add_f32_e32 v182, v182, v183
	v_add_f32_e32 v187, v187, v178
	v_add_f32_e32 v187, v187, v182
	s_waitcnt vmcnt(11)
	v_permlane16_swap_b32_e32 v92, v88
	v_permlane16_swap_b32_e32 v93, v89
	v_permlane16_swap_b32_e32 v94, v90
	v_permlane16_swap_b32_e32 v95, v91
	v_lshlrev_b32_e32 v178, 16, v156
	v_and_b32_e32 v179, 0xffff0000, v156
	v_lshlrev_b32_e32 v180, 16, v157
	v_and_b32_e32 v181, 0xffff0000, v157
	v_lshlrev_b32_e32 v182, 16, v158
	v_and_b32_e32 v183, 0xffff0000, v158
	v_lshlrev_b32_e32 v184, 16, v159
	v_and_b32_e32 v185, 0xffff0000, v159
	v_pk_fma_f32 v[92:93], s[14:15], v[92:93], v[178:179]
	v_pk_fma_f32 v[94:95], s[14:15], v[94:95], v[180:181]
	v_pk_fma_f32 v[88:89], s[14:15], v[88:89], v[182:183]
	v_pk_fma_f32 v[90:91], s[14:15], v[90:91], v[184:185]
	s_add_u32 s10, s0, 0x10000
	s_addc_u32 s11, s1, 0
	v_cvt_pk_bf16_f32 v156, v92, v93
	v_cvt_pk_bf16_f32 v157, v94, v95
	v_cvt_pk_bf16_f32 v158, v88, v89
	v_cvt_pk_bf16_f32 v159, v90, v91
	global_store_dwordx4 v136, v[156:159], s[10:11]
	s_add_u32 s10, s0, 0x50000
	s_addc_u32 s11, s1, 0
	global_load_dwordx4 v[92:95], v136, s[10:11]
	v_lshlrev_b32_e32 v178, 16, v156
	v_lshlrev_b32_e32 v179, 16, v157
	v_and_b32_e32 v180, 0xffff0000, v156
	v_and_b32_e32 v181, 0xffff0000, v157
	v_lshlrev_b32_e32 v182, 16, v158
	v_lshlrev_b32_e32 v183, 16, v159
	v_and_b32_e32 v184, 0xffff0000, v158
	v_and_b32_e32 v185, 0xffff0000, v159
	v_pk_mul_f32 v[180:181], v[180:181], v[180:181]
	v_pk_mul_f32 v[184:185], v[184:185], v[184:185]
	v_pk_fma_f32 v[178:179], v[178:179], v[178:179], v[180:181]
	v_pk_fma_f32 v[182:183], v[182:183], v[182:183], v[184:185]
	s_nop 0
	v_add_f32_e32 v178, v178, v179
	v_add_f32_e32 v182, v182, v183
	v_add_f32_e32 v188, v178, v182
	s_waitcnt vmcnt(12)
	v_permlane16_swap_b32_e32 v84, v80
	v_permlane16_swap_b32_e32 v85, v81
	v_permlane16_swap_b32_e32 v86, v82
	v_permlane16_swap_b32_e32 v87, v83
	v_lshlrev_b32_e32 v178, 16, v160
	v_and_b32_e32 v179, 0xffff0000, v160
	v_lshlrev_b32_e32 v180, 16, v161
	v_and_b32_e32 v181, 0xffff0000, v161
	v_lshlrev_b32_e32 v182, 16, v162
	v_and_b32_e32 v183, 0xffff0000, v162
	v_lshlrev_b32_e32 v184, 16, v163
	v_and_b32_e32 v185, 0xffff0000, v163
	v_pk_fma_f32 v[84:85], s[14:15], v[84:85], v[178:179]
	v_pk_fma_f32 v[86:87], s[14:15], v[86:87], v[180:181]
	v_pk_fma_f32 v[80:81], s[14:15], v[80:81], v[182:183]
	v_pk_fma_f32 v[82:83], s[14:15], v[82:83], v[184:185]
	s_add_u32 s10, s0, 0x10000
	s_addc_u32 s11, s1, 0
	v_cvt_pk_bf16_f32 v160, v84, v85
	v_cvt_pk_bf16_f32 v161, v86, v87
	v_cvt_pk_bf16_f32 v162, v80, v81
	v_cvt_pk_bf16_f32 v163, v82, v83
	global_store_dwordx4 v136, v[160:163], s[10:11] offset:256
	s_add_u32 s10, s0, 0x50000
	s_addc_u32 s11, s1, 0
	global_load_dwordx4 v[84:87], v136, s[10:11] offset:256
	v_lshlrev_b32_e32 v178, 16, v160
	v_lshlrev_b32_e32 v179, 16, v161
	v_and_b32_e32 v180, 0xffff0000, v160
	v_and_b32_e32 v181, 0xffff0000, v161
	v_lshlrev_b32_e32 v182, 16, v162
	v_lshlrev_b32_e32 v183, 16, v163
	v_and_b32_e32 v184, 0xffff0000, v162
	v_and_b32_e32 v185, 0xffff0000, v163
	v_pk_mul_f32 v[180:181], v[180:181], v[180:181]
	v_pk_mul_f32 v[184:185], v[184:185], v[184:185]
	v_pk_fma_f32 v[178:179], v[178:179], v[178:179], v[180:181]
	v_pk_fma_f32 v[182:183], v[182:183], v[182:183], v[184:185]
	s_nop 0
	v_add_f32_e32 v178, v178, v179
	v_add_f32_e32 v182, v182, v183
	v_add_f32_e32 v188, v188, v178
	v_add_f32_e32 v188, v188, v182
	s_waitcnt vmcnt(13)
	v_permlane16_swap_b32_e32 v76, v72
	v_permlane16_swap_b32_e32 v77, v73
	v_permlane16_swap_b32_e32 v78, v74
	v_permlane16_swap_b32_e32 v79, v75
	v_lshlrev_b32_e32 v178, 16, v164
	v_and_b32_e32 v179, 0xffff0000, v164
	v_lshlrev_b32_e32 v180, 16, v165
	v_and_b32_e32 v181, 0xffff0000, v165
	v_lshlrev_b32_e32 v182, 16, v166
	v_and_b32_e32 v183, 0xffff0000, v166
	v_lshlrev_b32_e32 v184, 16, v167
	v_and_b32_e32 v185, 0xffff0000, v167
	v_pk_fma_f32 v[76:77], s[14:15], v[76:77], v[178:179]
	v_pk_fma_f32 v[78:79], s[14:15], v[78:79], v[180:181]
	v_pk_fma_f32 v[72:73], s[14:15], v[72:73], v[182:183]
	v_pk_fma_f32 v[74:75], s[14:15], v[74:75], v[184:185]
	s_add_u32 s10, s0, 0x18000
	s_addc_u32 s11, s1, 0
	v_cvt_pk_bf16_f32 v164, v76, v77
	v_cvt_pk_bf16_f32 v165, v78, v79
	v_cvt_pk_bf16_f32 v166, v72, v73
	v_cvt_pk_bf16_f32 v167, v74, v75
	global_store_dwordx4 v136, v[164:167], s[10:11]
	s_add_u32 s10, s0, 0x58000
	s_addc_u32 s11, s1, 0
	global_load_dwordx4 v[76:79], v136, s[10:11]
	v_lshlrev_b32_e32 v178, 16, v164
	v_lshlrev_b32_e32 v179, 16, v165
	v_and_b32_e32 v180, 0xffff0000, v164
	v_and_b32_e32 v181, 0xffff0000, v165
	v_lshlrev_b32_e32 v182, 16, v166
	v_lshlrev_b32_e32 v183, 16, v167
	v_and_b32_e32 v184, 0xffff0000, v166
	v_and_b32_e32 v185, 0xffff0000, v167
	v_pk_mul_f32 v[180:181], v[180:181], v[180:181]
	v_pk_mul_f32 v[184:185], v[184:185], v[184:185]
	v_pk_fma_f32 v[178:179], v[178:179], v[178:179], v[180:181]
	v_pk_fma_f32 v[182:183], v[182:183], v[182:183], v[184:185]
	s_nop 0
	v_add_f32_e32 v178, v178, v179
	v_add_f32_e32 v182, v182, v183
	v_add_f32_e32 v189, v178, v182
	s_waitcnt vmcnt(14)
	v_permlane16_swap_b32_e32 v68, v64
	v_permlane16_swap_b32_e32 v69, v65
	v_permlane16_swap_b32_e32 v70, v66
	v_permlane16_swap_b32_e32 v71, v67
	v_lshlrev_b32_e32 v178, 16, v174
	v_and_b32_e32 v179, 0xffff0000, v174
	v_lshlrev_b32_e32 v180, 16, v175
	v_and_b32_e32 v181, 0xffff0000, v175
	v_lshlrev_b32_e32 v182, 16, v176
	v_and_b32_e32 v183, 0xffff0000, v176
	v_lshlrev_b32_e32 v184, 16, v177
	v_and_b32_e32 v185, 0xffff0000, v177
	v_pk_fma_f32 v[68:69], s[14:15], v[68:69], v[178:179]
	v_pk_fma_f32 v[70:71], s[14:15], v[70:71], v[180:181]
	v_pk_fma_f32 v[64:65], s[14:15], v[64:65], v[182:183]
	v_pk_fma_f32 v[66:67], s[14:15], v[66:67], v[184:185]
	s_add_u32 s10, s0, 0x18000
	s_addc_u32 s11, s1, 0
	v_cvt_pk_bf16_f32 v174, v68, v69
	v_cvt_pk_bf16_f32 v175, v70, v71
	v_cvt_pk_bf16_f32 v176, v64, v65
	v_cvt_pk_bf16_f32 v177, v66, v67
	global_store_dwordx4 v136, v[174:177], s[10:11] offset:256
	s_add_u32 s10, s0, 0x58000
	s_addc_u32 s11, s1, 0
	global_load_dwordx4 v[68:71], v136, s[10:11] offset:256
	v_lshlrev_b32_e32 v178, 16, v174
	v_lshlrev_b32_e32 v179, 16, v175
	v_and_b32_e32 v180, 0xffff0000, v174
	v_and_b32_e32 v181, 0xffff0000, v175
	v_lshlrev_b32_e32 v182, 16, v176
	v_lshlrev_b32_e32 v183, 16, v177
	v_and_b32_e32 v184, 0xffff0000, v176
	v_and_b32_e32 v185, 0xffff0000, v177
	v_pk_mul_f32 v[180:181], v[180:181], v[180:181]
	v_pk_mul_f32 v[184:185], v[184:185], v[184:185]
	v_pk_fma_f32 v[178:179], v[178:179], v[178:179], v[180:181]
	v_pk_fma_f32 v[182:183], v[182:183], v[182:183], v[184:185]
	s_nop 0
	v_add_f32_e32 v178, v178, v179
	v_add_f32_e32 v182, v182, v183
	v_add_f32_e32 v189, v189, v178
	v_add_f32_e32 v189, v189, v182
	ds_bpermute_b32 v178, v138, v186
	ds_bpermute_b32 v179, v138, v187
	ds_bpermute_b32 v180, v138, v188
	ds_bpermute_b32 v181, v138, v189
	s_waitcnt lgkmcnt(0)
	v_add_f32_e32 v186, v186, v178
	v_add_f32_e32 v187, v187, v179
	v_add_f32_e32 v188, v188, v180
	v_add_f32_e32 v189, v189, v181
	ds_bpermute_b32 v178, v139, v186
	ds_bpermute_b32 v179, v139, v187
	ds_bpermute_b32 v180, v139, v188
	ds_bpermute_b32 v181, v139, v189
	s_waitcnt lgkmcnt(0)
	v_add_f32_e32 v186, v186, v178
	v_add_f32_e32 v187, v187, v179
	v_add_f32_e32 v188, v188, v180
	v_add_f32_e32 v189, v189, v181
	s_and_saveexec_b64 vcc, s[4:5]
	ds_write_b32 v192, v186
	ds_write_b32 v192, v187 offset:256
	ds_write_b32 v192, v188 offset:512
	ds_write_b32 v192, v189 offset:768
	s_or_b64 exec, exec, vcc
	s_waitcnt vmcnt(14)
	v_permlane16_swap_b32_e32 v60, v56
	v_permlane16_swap_b32_e32 v61, v57
	v_permlane16_swap_b32_e32 v62, v58
	v_permlane16_swap_b32_e32 v63, v59
	v_lshlrev_b32_e32 v178, 16, v126
	v_and_b32_e32 v179, 0xffff0000, v126
	v_lshlrev_b32_e32 v180, 16, v127
	v_and_b32_e32 v181, 0xffff0000, v127
	v_lshlrev_b32_e32 v182, 16, v128
	v_and_b32_e32 v183, 0xffff0000, v128
	v_lshlrev_b32_e32 v184, 16, v129
	v_and_b32_e32 v185, 0xffff0000, v129
	v_pk_fma_f32 v[60:61], s[14:15], v[60:61], v[178:179]
	v_pk_fma_f32 v[62:63], s[14:15], v[62:63], v[180:181]
	v_pk_fma_f32 v[56:57], s[14:15], v[56:57], v[182:183]
	v_pk_fma_f32 v[58:59], s[14:15], v[58:59], v[184:185]
	s_add_u32 s10, s0, 0x40000
	s_addc_u32 s11, s1, 0
	v_cvt_pk_bf16_f32 v126, v60, v61
	v_cvt_pk_bf16_f32 v127, v62, v63
	v_cvt_pk_bf16_f32 v128, v56, v57
	v_cvt_pk_bf16_f32 v129, v58, v59
	global_store_dwordx4 v136, v[126:129], s[10:11]
	v_lshlrev_b32_e32 v178, 16, v126
	v_lshlrev_b32_e32 v179, 16, v127
	v_and_b32_e32 v180, 0xffff0000, v126
	v_and_b32_e32 v181, 0xffff0000, v127
	v_lshlrev_b32_e32 v182, 16, v128
	v_lshlrev_b32_e32 v183, 16, v129
	v_and_b32_e32 v184, 0xffff0000, v128
	v_and_b32_e32 v185, 0xffff0000, v129
	v_pk_mul_f32 v[180:181], v[180:181], v[180:181]
	v_pk_mul_f32 v[184:185], v[184:185], v[184:185]
	v_pk_fma_f32 v[178:179], v[178:179], v[178:179], v[180:181]
	v_pk_fma_f32 v[182:183], v[182:183], v[182:183], v[184:185]
	s_nop 0
	v_add_f32_e32 v178, v178, v179
	v_add_f32_e32 v182, v182, v183
	v_add_f32_e32 v186, v178, v182
	s_waitcnt vmcnt(13)
	v_permlane16_swap_b32_e32 v52, v48
	v_permlane16_swap_b32_e32 v53, v49
	v_permlane16_swap_b32_e32 v54, v50
	v_permlane16_swap_b32_e32 v55, v51
	v_lshlrev_b32_e32 v178, 16, v118
	v_and_b32_e32 v179, 0xffff0000, v118
	v_lshlrev_b32_e32 v180, 16, v119
	v_and_b32_e32 v181, 0xffff0000, v119
	v_lshlrev_b32_e32 v182, 16, v120
	v_and_b32_e32 v183, 0xffff0000, v120
	v_lshlrev_b32_e32 v184, 16, v121
	v_and_b32_e32 v185, 0xffff0000, v121
	v_pk_fma_f32 v[52:53], s[14:15], v[52:53], v[178:179]
	v_pk_fma_f32 v[54:55], s[14:15], v[54:55], v[180:181]
	v_pk_fma_f32 v[48:49], s[14:15], v[48:49], v[182:183]
	v_pk_fma_f32 v[50:51], s[14:15], v[50:51], v[184:185]
	s_add_u32 s10, s0, 0x40000
	s_addc_u32 s11, s1, 0
	v_cvt_pk_bf16_f32 v118, v52, v53
	v_cvt_pk_bf16_f32 v119, v54, v55
	v_cvt_pk_bf16_f32 v120, v48, v49
	v_cvt_pk_bf16_f32 v121, v50, v51
	global_store_dwordx4 v136, v[118:121], s[10:11] offset:256
	v_lshlrev_b32_e32 v178, 16, v118
	v_lshlrev_b32_e32 v179, 16, v119
	v_and_b32_e32 v180, 0xffff0000, v118
	v_and_b32_e32 v181, 0xffff0000, v119
	v_lshlrev_b32_e32 v182, 16, v120
	v_lshlrev_b32_e32 v183, 16, v121
	v_and_b32_e32 v184, 0xffff0000, v120
	v_and_b32_e32 v185, 0xffff0000, v121
	v_pk_mul_f32 v[180:181], v[180:181], v[180:181]
	v_pk_mul_f32 v[184:185], v[184:185], v[184:185]
	v_pk_fma_f32 v[178:179], v[178:179], v[178:179], v[180:181]
	v_pk_fma_f32 v[182:183], v[182:183], v[182:183], v[184:185]
	s_nop 0
	v_add_f32_e32 v178, v178, v179
	v_add_f32_e32 v182, v182, v183
	v_add_f32_e32 v186, v186, v178
	v_add_f32_e32 v186, v186, v182
	s_waitcnt vmcnt(12)
	v_permlane16_swap_b32_e32 v44, v40
	v_permlane16_swap_b32_e32 v45, v41
	v_permlane16_swap_b32_e32 v46, v42
	v_permlane16_swap_b32_e32 v47, v43
	v_lshlrev_b32_e32 v178, 16, v110
	v_and_b32_e32 v179, 0xffff0000, v110
	v_lshlrev_b32_e32 v180, 16, v111
	v_and_b32_e32 v181, 0xffff0000, v111
	v_lshlrev_b32_e32 v182, 16, v112
	v_and_b32_e32 v183, 0xffff0000, v112
	v_lshlrev_b32_e32 v184, 16, v113
	v_and_b32_e32 v185, 0xffff0000, v113
	v_pk_fma_f32 v[44:45], s[14:15], v[44:45], v[178:179]
	v_pk_fma_f32 v[46:47], s[14:15], v[46:47], v[180:181]
	v_pk_fma_f32 v[40:41], s[14:15], v[40:41], v[182:183]
	v_pk_fma_f32 v[42:43], s[14:15], v[42:43], v[184:185]
	s_add_u32 s10, s0, 0x48000
	s_addc_u32 s11, s1, 0
	v_cvt_pk_bf16_f32 v110, v44, v45
	v_cvt_pk_bf16_f32 v111, v46, v47
	v_cvt_pk_bf16_f32 v112, v40, v41
	v_cvt_pk_bf16_f32 v113, v42, v43
	global_store_dwordx4 v136, v[110:113], s[10:11]
	v_lshlrev_b32_e32 v178, 16, v110
	v_lshlrev_b32_e32 v179, 16, v111
	v_and_b32_e32 v180, 0xffff0000, v110
	v_and_b32_e32 v181, 0xffff0000, v111
	v_lshlrev_b32_e32 v182, 16, v112
	v_lshlrev_b32_e32 v183, 16, v113
	v_and_b32_e32 v184, 0xffff0000, v112
	v_and_b32_e32 v185, 0xffff0000, v113
	v_pk_mul_f32 v[180:181], v[180:181], v[180:181]
	v_pk_mul_f32 v[184:185], v[184:185], v[184:185]
	v_pk_fma_f32 v[178:179], v[178:179], v[178:179], v[180:181]
	v_pk_fma_f32 v[182:183], v[182:183], v[182:183], v[184:185]
	s_nop 0
	v_add_f32_e32 v178, v178, v179
	v_add_f32_e32 v182, v182, v183
	v_add_f32_e32 v187, v178, v182
	s_waitcnt vmcnt(11)
	v_permlane16_swap_b32_e32 v36, v32
	v_permlane16_swap_b32_e32 v37, v33
	v_permlane16_swap_b32_e32 v38, v34
	v_permlane16_swap_b32_e32 v39, v35
	v_lshlrev_b32_e32 v178, 16, v102
	v_and_b32_e32 v179, 0xffff0000, v102
	v_lshlrev_b32_e32 v180, 16, v103
	v_and_b32_e32 v181, 0xffff0000, v103
	v_lshlrev_b32_e32 v182, 16, v104
	v_and_b32_e32 v183, 0xffff0000, v104
	v_lshlrev_b32_e32 v184, 16, v105
	v_and_b32_e32 v185, 0xffff0000, v105
	v_pk_fma_f32 v[36:37], s[14:15], v[36:37], v[178:179]
	v_pk_fma_f32 v[38:39], s[14:15], v[38:39], v[180:181]
	v_pk_fma_f32 v[32:33], s[14:15], v[32:33], v[182:183]
	v_pk_fma_f32 v[34:35], s[14:15], v[34:35], v[184:185]
	s_add_u32 s10, s0, 0x48000
	s_addc_u32 s11, s1, 0
	v_cvt_pk_bf16_f32 v102, v36, v37
	v_cvt_pk_bf16_f32 v103, v38, v39
	v_cvt_pk_bf16_f32 v104, v32, v33
	v_cvt_pk_bf16_f32 v105, v34, v35
	global_store_dwordx4 v136, v[102:105], s[10:11] offset:256
	v_lshlrev_b32_e32 v178, 16, v102
	v_lshlrev_b32_e32 v179, 16, v103
	v_and_b32_e32 v180, 0xffff0000, v102
	v_and_b32_e32 v181, 0xffff0000, v103
	v_lshlrev_b32_e32 v182, 16, v104
	v_lshlrev_b32_e32 v183, 16, v105
	v_and_b32_e32 v184, 0xffff0000, v104
	v_and_b32_e32 v185, 0xffff0000, v105
	v_pk_mul_f32 v[180:181], v[180:181], v[180:181]
	v_pk_mul_f32 v[184:185], v[184:185], v[184:185]
	v_pk_fma_f32 v[178:179], v[178:179], v[178:179], v[180:181]
	v_pk_fma_f32 v[182:183], v[182:183], v[182:183], v[184:185]
	s_nop 0
	v_add_f32_e32 v178, v178, v179
	v_add_f32_e32 v182, v182, v183
	v_add_f32_e32 v187, v187, v178
	v_add_f32_e32 v187, v187, v182
	s_waitcnt vmcnt(10)
	v_permlane16_swap_b32_e32 v28, v24
	v_permlane16_swap_b32_e32 v29, v25
	v_permlane16_swap_b32_e32 v30, v26
	v_permlane16_swap_b32_e32 v31, v27
	v_lshlrev_b32_e32 v178, 16, v92
	v_and_b32_e32 v179, 0xffff0000, v92
	v_lshlrev_b32_e32 v180, 16, v93
	v_and_b32_e32 v181, 0xffff0000, v93
	v_lshlrev_b32_e32 v182, 16, v94
	v_and_b32_e32 v183, 0xffff0000, v94
	v_lshlrev_b32_e32 v184, 16, v95
	v_and_b32_e32 v185, 0xffff0000, v95
	v_pk_fma_f32 v[28:29], s[14:15], v[28:29], v[178:179]
	v_pk_fma_f32 v[30:31], s[14:15], v[30:31], v[180:181]
	v_pk_fma_f32 v[24:25], s[14:15], v[24:25], v[182:183]
	v_pk_fma_f32 v[26:27], s[14:15], v[26:27], v[184:185]
	s_add_u32 s10, s0, 0x50000
	s_addc_u32 s11, s1, 0
	v_cvt_pk_bf16_f32 v92, v28, v29
	v_cvt_pk_bf16_f32 v93, v30, v31
	v_cvt_pk_bf16_f32 v94, v24, v25
	v_cvt_pk_bf16_f32 v95, v26, v27
	global_store_dwordx4 v136, v[92:95], s[10:11]
	v_lshlrev_b32_e32 v178, 16, v92
	v_lshlrev_b32_e32 v179, 16, v93
	v_and_b32_e32 v180, 0xffff0000, v92
	v_and_b32_e32 v181, 0xffff0000, v93
	v_lshlrev_b32_e32 v182, 16, v94
	v_lshlrev_b32_e32 v183, 16, v95
	v_and_b32_e32 v184, 0xffff0000, v94
	v_and_b32_e32 v185, 0xffff0000, v95
	v_pk_mul_f32 v[180:181], v[180:181], v[180:181]
	v_pk_mul_f32 v[184:185], v[184:185], v[184:185]
	v_pk_fma_f32 v[178:179], v[178:179], v[178:179], v[180:181]
	v_pk_fma_f32 v[182:183], v[182:183], v[182:183], v[184:185]
	s_nop 0
	v_add_f32_e32 v178, v178, v179
	v_add_f32_e32 v182, v182, v183
	v_add_f32_e32 v188, v178, v182
	s_waitcnt vmcnt(9)
	v_permlane16_swap_b32_e32 v20, v16
	v_permlane16_swap_b32_e32 v21, v17
	v_permlane16_swap_b32_e32 v22, v18
	v_permlane16_swap_b32_e32 v23, v19
	v_lshlrev_b32_e32 v178, 16, v84
	v_and_b32_e32 v179, 0xffff0000, v84
	v_lshlrev_b32_e32 v180, 16, v85
	v_and_b32_e32 v181, 0xffff0000, v85
	v_lshlrev_b32_e32 v182, 16, v86
	v_and_b32_e32 v183, 0xffff0000, v86
	v_lshlrev_b32_e32 v184, 16, v87
	v_and_b32_e32 v185, 0xffff0000, v87
	v_pk_fma_f32 v[20:21], s[14:15], v[20:21], v[178:179]
	v_pk_fma_f32 v[22:23], s[14:15], v[22:23], v[180:181]
	v_pk_fma_f32 v[16:17], s[14:15], v[16:17], v[182:183]
	v_pk_fma_f32 v[18:19], s[14:15], v[18:19], v[184:185]
	s_add_u32 s10, s0, 0x50000
	s_addc_u32 s11, s1, 0
	v_cvt_pk_bf16_f32 v84, v20, v21
	v_cvt_pk_bf16_f32 v85, v22, v23
	v_cvt_pk_bf16_f32 v86, v16, v17
	v_cvt_pk_bf16_f32 v87, v18, v19
	global_store_dwordx4 v136, v[84:87], s[10:11] offset:256
	v_lshlrev_b32_e32 v178, 16, v84
	v_lshlrev_b32_e32 v179, 16, v85
	v_and_b32_e32 v180, 0xffff0000, v84
	v_and_b32_e32 v181, 0xffff0000, v85
	v_lshlrev_b32_e32 v182, 16, v86
	v_lshlrev_b32_e32 v183, 16, v87
	v_and_b32_e32 v184, 0xffff0000, v86
	v_and_b32_e32 v185, 0xffff0000, v87
	v_pk_mul_f32 v[180:181], v[180:181], v[180:181]
	v_pk_mul_f32 v[184:185], v[184:185], v[184:185]
	v_pk_fma_f32 v[178:179], v[178:179], v[178:179], v[180:181]
	v_pk_fma_f32 v[182:183], v[182:183], v[182:183], v[184:185]
	s_nop 0
	v_add_f32_e32 v178, v178, v179
	v_add_f32_e32 v182, v182, v183
	v_add_f32_e32 v188, v188, v178
	v_add_f32_e32 v188, v188, v182
	s_waitcnt vmcnt(8)
	v_permlane16_swap_b32_e32 v12, v8
	v_permlane16_swap_b32_e32 v13, v9
	v_permlane16_swap_b32_e32 v14, v10
	v_permlane16_swap_b32_e32 v15, v11
	v_lshlrev_b32_e32 v178, 16, v76
	v_and_b32_e32 v179, 0xffff0000, v76
	v_lshlrev_b32_e32 v180, 16, v77
	v_and_b32_e32 v181, 0xffff0000, v77
	v_lshlrev_b32_e32 v182, 16, v78
	v_and_b32_e32 v183, 0xffff0000, v78
	v_lshlrev_b32_e32 v184, 16, v79
	v_and_b32_e32 v185, 0xffff0000, v79
	v_pk_fma_f32 v[12:13], s[14:15], v[12:13], v[178:179]
	v_pk_fma_f32 v[14:15], s[14:15], v[14:15], v[180:181]
	v_pk_fma_f32 v[8:9], s[14:15], v[8:9], v[182:183]
	v_pk_fma_f32 v[10:11], s[14:15], v[10:11], v[184:185]
	s_add_u32 s10, s0, 0x58000
	s_addc_u32 s11, s1, 0
	v_cvt_pk_bf16_f32 v76, v12, v13
	v_cvt_pk_bf16_f32 v77, v14, v15
	v_cvt_pk_bf16_f32 v78, v8, v9
	v_cvt_pk_bf16_f32 v79, v10, v11
	global_store_dwordx4 v136, v[76:79], s[10:11]
	v_lshlrev_b32_e32 v178, 16, v76
	v_lshlrev_b32_e32 v179, 16, v77
	v_and_b32_e32 v180, 0xffff0000, v76
	v_and_b32_e32 v181, 0xffff0000, v77
	v_lshlrev_b32_e32 v182, 16, v78
	v_lshlrev_b32_e32 v183, 16, v79
	v_and_b32_e32 v184, 0xffff0000, v78
	v_and_b32_e32 v185, 0xffff0000, v79
	v_pk_mul_f32 v[180:181], v[180:181], v[180:181]
	v_pk_mul_f32 v[184:185], v[184:185], v[184:185]
	v_pk_fma_f32 v[178:179], v[178:179], v[178:179], v[180:181]
	v_pk_fma_f32 v[182:183], v[182:183], v[182:183], v[184:185]
	s_nop 0
	v_add_f32_e32 v178, v178, v179
	v_add_f32_e32 v182, v182, v183
	v_add_f32_e32 v189, v178, v182
	s_waitcnt vmcnt(7)
	v_permlane16_swap_b32_e32 v4, v0
	v_permlane16_swap_b32_e32 v5, v1
	v_permlane16_swap_b32_e32 v6, v2
	v_permlane16_swap_b32_e32 v7, v3
	v_lshlrev_b32_e32 v178, 16, v68
	v_and_b32_e32 v179, 0xffff0000, v68
	v_lshlrev_b32_e32 v180, 16, v69
	v_and_b32_e32 v181, 0xffff0000, v69
	v_lshlrev_b32_e32 v182, 16, v70
	v_and_b32_e32 v183, 0xffff0000, v70
	v_lshlrev_b32_e32 v184, 16, v71
	v_and_b32_e32 v185, 0xffff0000, v71
	v_pk_fma_f32 v[4:5], s[14:15], v[4:5], v[178:179]
	v_pk_fma_f32 v[6:7], s[14:15], v[6:7], v[180:181]
	v_pk_fma_f32 v[0:1], s[14:15], v[0:1], v[182:183]
	v_pk_fma_f32 v[2:3], s[14:15], v[2:3], v[184:185]
	s_add_u32 s10, s0, 0x58000
	s_addc_u32 s11, s1, 0
	v_cvt_pk_bf16_f32 v68, v4, v5
	v_cvt_pk_bf16_f32 v69, v6, v7
	v_cvt_pk_bf16_f32 v70, v0, v1
	v_cvt_pk_bf16_f32 v71, v2, v3
	global_store_dwordx4 v136, v[68:71], s[10:11] offset:256
	v_lshlrev_b32_e32 v178, 16, v68
	v_lshlrev_b32_e32 v179, 16, v69
	v_and_b32_e32 v180, 0xffff0000, v68
	v_and_b32_e32 v181, 0xffff0000, v69
	v_lshlrev_b32_e32 v182, 16, v70
	v_lshlrev_b32_e32 v183, 16, v71
	v_and_b32_e32 v184, 0xffff0000, v70
	v_and_b32_e32 v185, 0xffff0000, v71
	v_pk_mul_f32 v[180:181], v[180:181], v[180:181]
	v_pk_mul_f32 v[184:185], v[184:185], v[184:185]
	v_pk_fma_f32 v[178:179], v[178:179], v[178:179], v[180:181]
	v_pk_fma_f32 v[182:183], v[182:183], v[182:183], v[184:185]
	s_nop 0
	v_add_f32_e32 v178, v178, v179
	v_add_f32_e32 v182, v182, v183
	v_add_f32_e32 v189, v189, v178
	v_add_f32_e32 v189, v189, v182
	ds_bpermute_b32 v178, v138, v186
	ds_bpermute_b32 v179, v138, v187
	ds_bpermute_b32 v180, v138, v188
	ds_bpermute_b32 v181, v138, v189
	s_waitcnt lgkmcnt(0)
	v_add_f32_e32 v186, v186, v178
	v_add_f32_e32 v187, v187, v179
	v_add_f32_e32 v188, v188, v180
	v_add_f32_e32 v189, v189, v181
	ds_bpermute_b32 v178, v139, v186
	ds_bpermute_b32 v179, v139, v187
	ds_bpermute_b32 v180, v139, v188
	ds_bpermute_b32 v181, v139, v189
	s_waitcnt lgkmcnt(0)
	v_add_f32_e32 v186, v186, v178
	v_add_f32_e32 v187, v187, v179
	v_add_f32_e32 v188, v188, v180
	v_add_f32_e32 v189, v189, v181
	s_and_saveexec_b64 vcc, s[4:5]
	ds_write_b32 v192, v186 offset:2048
	ds_write_b32 v192, v187 offset:2304
	ds_write_b32 v192, v188 offset:2560
	ds_write_b32 v192, v189 offset:2816
	s_or_b64 exec, exec, vcc
	s_branch .LBB0_1107
.Lresid_fin:
	s_add_u32 s10, s0, 0x0
	s_addc_u32 s11, s1, 0
	global_load_dwordx4 v[140:143], v136, s[10:11]
	global_load_dwordx4 v[144:147], v136, s[10:11] offset:256
	s_add_u32 s10, s0, 0x8000
	s_addc_u32 s11, s1, 0
	global_load_dwordx4 v[148:151], v136, s[10:11]
	global_load_dwordx4 v[152:155], v136, s[10:11] offset:256
	s_add_u32 s10, s0, 0x10000
	s_addc_u32 s11, s1, 0
	global_load_dwordx4 v[156:159], v136, s[10:11]
	global_load_dwordx4 v[160:163], v136, s[10:11] offset:256
	s_add_u32 s10, s0, 0x18000
	s_addc_u32 s11, s1, 0
	global_load_dwordx4 v[164:167], v136, s[10:11]
	global_load_dwordx4 v[174:177], v136, s[10:11] offset:256
	s_waitcnt vmcnt(7)
	v_permlane16_swap_b32_e32 v126, v122
	v_permlane16_swap_b32_e32 v127, v123
	v_permlane16_swap_b32_e32 v128, v124
	v_permlane16_swap_b32_e32 v129, v125
	v_lshlrev_b32_e32 v178, 16, v140
	v_and_b32_e32 v179, 0xffff0000, v140
	v_lshlrev_b32_e32 v180, 16, v141
	v_and_b32_e32 v181, 0xffff0000, v141
	v_lshlrev_b32_e32 v182, 16, v142
	v_and_b32_e32 v183, 0xffff0000, v142
	v_lshlrev_b32_e32 v184, 16, v143
	v_and_b32_e32 v185, 0xffff0000, v143
	v_pk_fma_f32 v[126:127], s[14:15], v[126:127], v[178:179]
	v_pk_fma_f32 v[128:129], s[14:15], v[128:129], v[180:181]
	v_pk_fma_f32 v[122:123], s[14:15], v[122:123], v[182:183]
	v_pk_fma_f32 v[124:125], s[14:15], v[124:125], v[184:185]
	s_add_u32 s10, s16, 0x0
	s_addc_u32 s11, s17, 0
	global_store_dwordx4 v137, v[126:129], s[10:11] offset:0
	global_store_dwordx4 v137, v[122:125], s[10:11] offset:16
	s_add_u32 s10, s0, 0x40000
	s_addc_u32 s11, s1, 0
	global_load_dwordx4 v[140:143], v136, s[10:11]
	s_waitcnt vmcnt(9)
	v_permlane16_swap_b32_e32 v118, v114
	v_permlane16_swap_b32_e32 v119, v115
	v_permlane16_swap_b32_e32 v120, v116
	v_permlane16_swap_b32_e32 v121, v117
	v_lshlrev_b32_e32 v178, 16, v144
	v_and_b32_e32 v179, 0xffff0000, v144
	v_lshlrev_b32_e32 v180, 16, v145
	v_and_b32_e32 v181, 0xffff0000, v145
	v_lshlrev_b32_e32 v182, 16, v146
	v_and_b32_e32 v183, 0xffff0000, v146
	v_lshlrev_b32_e32 v184, 16, v147
	v_and_b32_e32 v185, 0xffff0000, v147
	v_pk_fma_f32 v[118:119], s[14:15], v[118:119], v[178:179]
	v_pk_fma_f32 v[120:121], s[14:15], v[120:121], v[180:181]
	v_pk_fma_f32 v[114:115], s[14:15], v[114:115], v[182:183]
	v_pk_fma_f32 v[116:117], s[14:15], v[116:117], v[184:185]
	s_add_u32 s10, s16, 0x0
	s_addc_u32 s11, s17, 0
	global_store_dwordx4 v137, v[118:121], s[10:11] offset:512
	global_store_dwordx4 v137, v[114:117], s[10:11] offset:528
	s_add_u32 s10, s0, 0x40000
	s_addc_u32 s11, s1, 0
	global_load_dwordx4 v[144:147], v136, s[10:11] offset:256
	s_waitcnt vmcnt(11)
	v_permlane16_swap_b32_e32 v110, v106
	v_permlane16_swap_b32_e32 v111, v107
	v_permlane16_swap_b32_e32 v112, v108
	v_permlane16_swap_b32_e32 v113, v109
	v_lshlrev_b32_e32 v178, 16, v148
	v_and_b32_e32 v179, 0xffff0000, v148
	v_lshlrev_b32_e32 v180, 16, v149
	v_and_b32_e32 v181, 0xffff0000, v149
	v_lshlrev_b32_e32 v182, 16, v150
	v_and_b32_e32 v183, 0xffff0000, v150
	v_lshlrev_b32_e32 v184, 16, v151
	v_and_b32_e32 v185, 0xffff0000, v151
	v_pk_fma_f32 v[110:111], s[14:15], v[110:111], v[178:179]
	v_pk_fma_f32 v[112:113], s[14:15], v[112:113], v[180:181]
	v_pk_fma_f32 v[106:107], s[14:15], v[106:107], v[182:183]
	v_pk_fma_f32 v[108:109], s[14:15], v[108:109], v[184:185]
	s_add_u32 s10, s16, 0x10000
	s_addc_u32 s11, s17, 0
	global_store_dwordx4 v137, v[110:113], s[10:11] offset:0
	global_store_dwordx4 v137, v[106:109], s[10:11] offset:16
	s_add_u32 s10, s0, 0x48000
	s_addc_u32 s11, s1, 0
	global_load_dwordx4 v[148:151], v136, s[10:11]
	s_waitcnt vmcnt(13)
	v_permlane16_swap_b32_e32 v102, v98
	v_permlane16_swap_b32_e32 v103, v99
	v_permlane16_swap_b32_e32 v104, v100
	v_permlane16_swap_b32_e32 v105, v101
	v_lshlrev_b32_e32 v178, 16, v152
	v_and_b32_e32 v179, 0xffff0000, v152
	v_lshlrev_b32_e32 v180, 16, v153
	v_and_b32_e32 v181, 0xffff0000, v153
	v_lshlrev_b32_e32 v182, 16, v154
	v_and_b32_e32 v183, 0xffff0000, v154
	v_lshlrev_b32_e32 v184, 16, v155
	v_and_b32_e32 v185, 0xffff0000, v155
	v_pk_fma_f32 v[102:103], s[14:15], v[102:103], v[178:179]
	v_pk_fma_f32 v[104:105], s[14:15], v[104:105], v[180:181]
	v_pk_fma_f32 v[98:99], s[14:15], v[98:99], v[182:183]
	v_pk_fma_f32 v[100:101], s[14:15], v[100:101], v[184:185]
	s_add_u32 s10, s16, 0x10000
	s_addc_u32 s11, s17, 0
	global_store_dwordx4 v137, v[102:105], s[10:11] offset:512
	global_store_dwordx4 v137, v[98:101], s[10:11] offset:528
	s_add_u32 s10, s0, 0x48000
	s_addc_u32 s11, s1, 0
	global_load_dwordx4 v[152:155], v136, s[10:11] offset:256
	s_waitcnt vmcnt(15)
	v_permlane16_swap_b32_e32 v92, v88
	v_permlane16_swap_b32_e32 v93, v89
	v_permlane16_swap_b32_e32 v94, v90
	v_permlane16_swap_b32_e32 v95, v91
	v_lshlrev_b32_e32 v178, 16, v156
	v_and_b32_e32 v179, 0xffff0000, v156
	v_lshlrev_b32_e32 v180, 16, v157
	v_and_b32_e32 v181, 0xffff0000, v157
	v_lshlrev_b32_e32 v182, 16, v158
	v_and_b32_e32 v183, 0xffff0000, v158
	v_lshlrev_b32_e32 v184, 16, v159
	v_and_b32_e32 v185, 0xffff0000, v159
	v_pk_fma_f32 v[92:93], s[14:15], v[92:93], v[178:179]
	v_pk_fma_f32 v[94:95], s[14:15], v[94:95], v[180:181]
	v_pk_fma_f32 v[88:89], s[14:15], v[88:89], v[182:183]
	v_pk_fma_f32 v[90:91], s[14:15], v[90:91], v[184:185]
	s_add_u32 s10, s16, 0x20000
	s_addc_u32 s11, s17, 0
	global_store_dwordx4 v137, v[92:95], s[10:11] offset:0
	global_store_dwordx4 v137, v[88:91], s[10:11] offset:16
	s_add_u32 s10, s0, 0x50000
	s_addc_u32 s11, s1, 0
	global_load_dwordx4 v[156:159], v136, s[10:11]
	s_waitcnt vmcnt(17)
	v_permlane16_swap_b32_e32 v84, v80
	v_permlane16_swap_b32_e32 v85, v81
	v_permlane16_swap_b32_e32 v86, v82
	v_permlane16_swap_b32_e32 v87, v83
	v_lshlrev_b32_e32 v178, 16, v160
	v_and_b32_e32 v179, 0xffff0000, v160
	v_lshlrev_b32_e32 v180, 16, v161
	v_and_b32_e32 v181, 0xffff0000, v161
	v_lshlrev_b32_e32 v182, 16, v162
	v_and_b32_e32 v183, 0xffff0000, v162
	v_lshlrev_b32_e32 v184, 16, v163
	v_and_b32_e32 v185, 0xffff0000, v163
	v_pk_fma_f32 v[84:85], s[14:15], v[84:85], v[178:179]
	v_pk_fma_f32 v[86:87], s[14:15], v[86:87], v[180:181]
	v_pk_fma_f32 v[80:81], s[14:15], v[80:81], v[182:183]
	v_pk_fma_f32 v[82:83], s[14:15], v[82:83], v[184:185]
	s_add_u32 s10, s16, 0x20000
	s_addc_u32 s11, s17, 0
	global_store_dwordx4 v137, v[84:87], s[10:11] offset:512
	global_store_dwordx4 v137, v[80:83], s[10:11] offset:528
	s_add_u32 s10, s0, 0x50000
	s_addc_u32 s11, s1, 0
	global_load_dwordx4 v[160:163], v136, s[10:11] offset:256
	s_waitcnt vmcnt(19)
	v_permlane16_swap_b32_e32 v76, v72
	v_permlane16_swap_b32_e32 v77, v73
	v_permlane16_swap_b32_e32 v78, v74
	v_permlane16_swap_b32_e32 v79, v75
	v_lshlrev_b32_e32 v178, 16, v164
	v_and_b32_e32 v179, 0xffff0000, v164
	v_lshlrev_b32_e32 v180, 16, v165
	v_and_b32_e32 v181, 0xffff0000, v165
	v_lshlrev_b32_e32 v182, 16, v166
	v_and_b32_e32 v183, 0xffff0000, v166
	v_lshlrev_b32_e32 v184, 16, v167
	v_and_b32_e32 v185, 0xffff0000, v167
	v_pk_fma_f32 v[76:77], s[14:15], v[76:77], v[178:179]
	v_pk_fma_f32 v[78:79], s[14:15], v[78:79], v[180:181]
	v_pk_fma_f32 v[72:73], s[14:15], v[72:73], v[182:183]
	v_pk_fma_f32 v[74:75], s[14:15], v[74:75], v[184:185]
	s_add_u32 s10, s16, 0x30000
	s_addc_u32 s11, s17, 0
	global_store_dwordx4 v137, v[76:79], s[10:11] offset:0
	global_store_dwordx4 v137, v[72:75], s[10:11] offset:16
	s_add_u32 s10, s0, 0x58000
	s_addc_u32 s11, s1, 0
	global_load_dwordx4 v[164:167], v136, s[10:11]
	s_waitcnt vmcnt(21)
	v_permlane16_swap_b32_e32 v68, v64
	v_permlane16_swap_b32_e32 v69, v65
	v_permlane16_swap_b32_e32 v70, v66
	v_permlane16_swap_b32_e32 v71, v67
	v_lshlrev_b32_e32 v178, 16, v174
	v_and_b32_e32 v179, 0xffff0000, v174
	v_lshlrev_b32_e32 v180, 16, v175
	v_and_b32_e32 v181, 0xffff0000, v175
	v_lshlrev_b32_e32 v182, 16, v176
	v_and_b32_e32 v183, 0xffff0000, v176
	v_lshlrev_b32_e32 v184, 16, v177
	v_and_b32_e32 v185, 0xffff0000, v177
	v_pk_fma_f32 v[68:69], s[14:15], v[68:69], v[178:179]
	v_pk_fma_f32 v[70:71], s[14:15], v[70:71], v[180:181]
	v_pk_fma_f32 v[64:65], s[14:15], v[64:65], v[182:183]
	v_pk_fma_f32 v[66:67], s[14:15], v[66:67], v[184:185]
	s_add_u32 s10, s16, 0x30000
	s_addc_u32 s11, s17, 0
	global_store_dwordx4 v137, v[68:71], s[10:11] offset:512
	global_store_dwordx4 v137, v[64:67], s[10:11] offset:528
	s_add_u32 s10, s0, 0x58000
	s_addc_u32 s11, s1, 0
	global_load_dwordx4 v[174:177], v136, s[10:11] offset:256
	s_waitcnt vmcnt(21)
	v_permlane16_swap_b32_e32 v60, v56
	v_permlane16_swap_b32_e32 v61, v57
	v_permlane16_swap_b32_e32 v62, v58
	v_permlane16_swap_b32_e32 v63, v59
	v_lshlrev_b32_e32 v178, 16, v140
	v_and_b32_e32 v179, 0xffff0000, v140
	v_lshlrev_b32_e32 v180, 16, v141
	v_and_b32_e32 v181, 0xffff0000, v141
	v_lshlrev_b32_e32 v182, 16, v142
	v_and_b32_e32 v183, 0xffff0000, v142
	v_lshlrev_b32_e32 v184, 16, v143
	v_and_b32_e32 v185, 0xffff0000, v143
	v_pk_fma_f32 v[60:61], s[14:15], v[60:61], v[178:179]
	v_pk_fma_f32 v[62:63], s[14:15], v[62:63], v[180:181]
	v_pk_fma_f32 v[56:57], s[14:15], v[56:57], v[182:183]
	v_pk_fma_f32 v[58:59], s[14:15], v[58:59], v[184:185]
	s_add_u32 s10, s16, 0x80000
	s_addc_u32 s11, s17, 0
	global_store_dwordx4 v137, v[60:63], s[10:11] offset:0
	global_store_dwordx4 v137, v[56:59], s[10:11] offset:16
	s_waitcnt vmcnt(20)
	v_permlane16_swap_b32_e32 v52, v48
	v_permlane16_swap_b32_e32 v53, v49
	v_permlane16_swap_b32_e32 v54, v50
	v_permlane16_swap_b32_e32 v55, v51
	v_lshlrev_b32_e32 v178, 16, v144
	v_and_b32_e32 v179, 0xffff0000, v144
	v_lshlrev_b32_e32 v180, 16, v145
	v_and_b32_e32 v181, 0xffff0000, v145
	v_lshlrev_b32_e32 v182, 16, v146
	v_and_b32_e32 v183, 0xffff0000, v146
	v_lshlrev_b32_e32 v184, 16, v147
	v_and_b32_e32 v185, 0xffff0000, v147
	v_pk_fma_f32 v[52:53], s[14:15], v[52:53], v[178:179]
	v_pk_fma_f32 v[54:55], s[14:15], v[54:55], v[180:181]
	v_pk_fma_f32 v[48:49], s[14:15], v[48:49], v[182:183]
	v_pk_fma_f32 v[50:51], s[14:15], v[50:51], v[184:185]
	s_add_u32 s10, s16, 0x80000
	s_addc_u32 s11, s17, 0
	global_store_dwordx4 v137, v[52:55], s[10:11] offset:512
	global_store_dwordx4 v137, v[48:51], s[10:11] offset:528
	s_waitcnt vmcnt(19)
	v_permlane16_swap_b32_e32 v44, v40
	v_permlane16_swap_b32_e32 v45, v41
	v_permlane16_swap_b32_e32 v46, v42
	v_permlane16_swap_b32_e32 v47, v43
	v_lshlrev_b32_e32 v178, 16, v148
	v_and_b32_e32 v179, 0xffff0000, v148
	v_lshlrev_b32_e32 v180, 16, v149
	v_and_b32_e32 v181, 0xffff0000, v149
	v_lshlrev_b32_e32 v182, 16, v150
	v_and_b32_e32 v183, 0xffff0000, v150
	v_lshlrev_b32_e32 v184, 16, v151
	v_and_b32_e32 v185, 0xffff0000, v151
	v_pk_fma_f32 v[44:45], s[14:15], v[44:45], v[178:179]
	v_pk_fma_f32 v[46:47], s[14:15], v[46:47], v[180:181]
	v_pk_fma_f32 v[40:41], s[14:15], v[40:41], v[182:183]
	v_pk_fma_f32 v[42:43], s[14:15], v[42:43], v[184:185]
	s_add_u32 s10, s16, 0x90000
	s_addc_u32 s11, s17, 0
	global_store_dwordx4 v137, v[44:47], s[10:11] offset:0
	global_store_dwordx4 v137, v[40:43], s[10:11] offset:16
	s_waitcnt vmcnt(18)
	v_permlane16_swap_b32_e32 v36, v32
	v_permlane16_swap_b32_e32 v37, v33
	v_permlane16_swap_b32_e32 v38, v34
	v_permlane16_swap_b32_e32 v39, v35
	v_lshlrev_b32_e32 v178, 16, v152
	v_and_b32_e32 v179, 0xffff0000, v152
	v_lshlrev_b32_e32 v180, 16, v153
	v_and_b32_e32 v181, 0xffff0000, v153
	v_lshlrev_b32_e32 v182, 16, v154
	v_and_b32_e32 v183, 0xffff0000, v154
	v_lshlrev_b32_e32 v184, 16, v155
	v_and_b32_e32 v185, 0xffff0000, v155
	v_pk_fma_f32 v[36:37], s[14:15], v[36:37], v[178:179]
	v_pk_fma_f32 v[38:39], s[14:15], v[38:39], v[180:181]
	v_pk_fma_f32 v[32:33], s[14:15], v[32:33], v[182:183]
	v_pk_fma_f32 v[34:35], s[14:15], v[34:35], v[184:185]
	s_add_u32 s10, s16, 0x90000
	s_addc_u32 s11, s17, 0
	global_store_dwordx4 v137, v[36:39], s[10:11] offset:512
	global_store_dwordx4 v137, v[32:35], s[10:11] offset:528
	s_waitcnt vmcnt(17)
	v_permlane16_swap_b32_e32 v28, v24
	v_permlane16_swap_b32_e32 v29, v25
	v_permlane16_swap_b32_e32 v30, v26
	v_permlane16_swap_b32_e32 v31, v27
	v_lshlrev_b32_e32 v178, 16, v156
	v_and_b32_e32 v179, 0xffff0000, v156
	v_lshlrev_b32_e32 v180, 16, v157
	v_and_b32_e32 v181, 0xffff0000, v157
	v_lshlrev_b32_e32 v182, 16, v158
	v_and_b32_e32 v183, 0xffff0000, v158
	v_lshlrev_b32_e32 v184, 16, v159
	v_and_b32_e32 v185, 0xffff0000, v159
	v_pk_fma_f32 v[28:29], s[14:15], v[28:29], v[178:179]
	v_pk_fma_f32 v[30:31], s[14:15], v[30:31], v[180:181]
	v_pk_fma_f32 v[24:25], s[14:15], v[24:25], v[182:183]
	v_pk_fma_f32 v[26:27], s[14:15], v[26:27], v[184:185]
	s_add_u32 s10, s16, 0xa0000
	s_addc_u32 s11, s17, 0
	global_store_dwordx4 v137, v[28:31], s[10:11] offset:0
	global_store_dwordx4 v137, v[24:27], s[10:11] offset:16
	s_waitcnt vmcnt(16)
	v_permlane16_swap_b32_e32 v20, v16
	v_permlane16_swap_b32_e32 v21, v17
	v_permlane16_swap_b32_e32 v22, v18
	v_permlane16_swap_b32_e32 v23, v19
	v_lshlrev_b32_e32 v178, 16, v160
	v_and_b32_e32 v179, 0xffff0000, v160
	v_lshlrev_b32_e32 v180, 16, v161
	v_and_b32_e32 v181, 0xffff0000, v161
	v_lshlrev_b32_e32 v182, 16, v162
	v_and_b32_e32 v183, 0xffff0000, v162
	v_lshlrev_b32_e32 v184, 16, v163
	v_and_b32_e32 v185, 0xffff0000, v163
	v_pk_fma_f32 v[20:21], s[14:15], v[20:21], v[178:179]
	v_pk_fma_f32 v[22:23], s[14:15], v[22:23], v[180:181]
	v_pk_fma_f32 v[16:17], s[14:15], v[16:17], v[182:183]
	v_pk_fma_f32 v[18:19], s[14:15], v[18:19], v[184:185]
	s_add_u32 s10, s16, 0xa0000
	s_addc_u32 s11, s17, 0
	global_store_dwordx4 v137, v[20:23], s[10:11] offset:512
	global_store_dwordx4 v137, v[16:19], s[10:11] offset:528
	s_waitcnt vmcnt(15)
	v_permlane16_swap_b32_e32 v12, v8
	v_permlane16_swap_b32_e32 v13, v9
	v_permlane16_swap_b32_e32 v14, v10
	v_permlane16_swap_b32_e32 v15, v11
	v_lshlrev_b32_e32 v178, 16, v164
	v_and_b32_e32 v179, 0xffff0000, v164
	v_lshlrev_b32_e32 v180, 16, v165
	v_and_b32_e32 v181, 0xffff0000, v165
	v_lshlrev_b32_e32 v182, 16, v166
	v_and_b32_e32 v183, 0xffff0000, v166
	v_lshlrev_b32_e32 v184, 16, v167
	v_and_b32_e32 v185, 0xffff0000, v167
	v_pk_fma_f32 v[12:13], s[14:15], v[12:13], v[178:179]
	v_pk_fma_f32 v[14:15], s[14:15], v[14:15], v[180:181]
	v_pk_fma_f32 v[8:9], s[14:15], v[8:9], v[182:183]
	v_pk_fma_f32 v[10:11], s[14:15], v[10:11], v[184:185]
	s_add_u32 s10, s16, 0xb0000
	s_addc_u32 s11, s17, 0
	global_store_dwordx4 v137, v[12:15], s[10:11] offset:0
	global_store_dwordx4 v137, v[8:11], s[10:11] offset:16
	s_waitcnt vmcnt(14)
	v_permlane16_swap_b32_e32 v4, v0
	v_permlane16_swap_b32_e32 v5, v1
	v_permlane16_swap_b32_e32 v6, v2
	v_permlane16_swap_b32_e32 v7, v3
	v_lshlrev_b32_e32 v178, 16, v174
	v_and_b32_e32 v179, 0xffff0000, v174
	v_lshlrev_b32_e32 v180, 16, v175
	v_and_b32_e32 v181, 0xffff0000, v175
	v_lshlrev_b32_e32 v182, 16, v176
	v_and_b32_e32 v183, 0xffff0000, v176
	v_lshlrev_b32_e32 v184, 16, v177
	v_and_b32_e32 v185, 0xffff0000, v177
	v_pk_fma_f32 v[4:5], s[14:15], v[4:5], v[178:179]
	v_pk_fma_f32 v[6:7], s[14:15], v[6:7], v[180:181]
	v_pk_fma_f32 v[0:1], s[14:15], v[0:1], v[182:183]
	v_pk_fma_f32 v[2:3], s[14:15], v[2:3], v[184:185]
	s_add_u32 s10, s16, 0xb0000
	s_addc_u32 s11, s17, 0
	global_store_dwordx4 v137, v[4:7], s[10:11] offset:512
	global_store_dwordx4 v137, v[0:3], s[10:11] offset:528
